# v15 plus non-temporal hint on the final f32 output stores of the last phase
# baseline (speedup 1.0000x reference)
;     __device__ __forceinline__ void operator()(const f32x4 (&acc)[2][2][4][2], const Unit& u, int wr, int wc, int fr, int fq) const {
;     ...
;                         if (base_bf) { const u32x4 t = *(const u32x4*)(base_bf + off + bj * HALF);
;                             b0 = (f32x4){__uint_as_float(t.x << 16), __uint_as_float(t.x & 0xffff0000u), __uint_as_float(t.y << 16), __uint_as_float(t.y & 0xffff0000u)};
;                             b1 = (f32x4){__uint_as_float(t.z << 16), __uint_as_float(t.z & 0xffff0000u), __uint_as_float(t.w << 16), __uint_as_float(t.w & 0xffff0000u)}; }
;                         else { b0 = *(const f32x4*)(base + off + bj * HALF); b1 = *(const f32x4*)(base + off + bj * HALF + 4); }
;                         const f32x4 o0 = b0 + acc[ai][bj][m][0] * alpha, o1 = b1 + acc[ai][bj][m][1] * alpha;
;                         if (out) { *(f32x4*)(out + off + bj * HALF) = o0; *(f32x4*)(out + off + bj * HALF + 4) = o1; }
.Lepi3_p9:
	v_lshl_or_b32 v244, s19, 8, v187
	v_mul_lo_u32 v245, s86, v156
	v_add_u32_e32 v244, v244, v245
	v_lshlrev_b32_e32 v174, 1, v244
	v_and_b32_e32 v246, -16, v156
	v_lshrrev_b32_e32 v247, 3, v217
	v_add_u32_e32 v246, v246, v247
	v_and_b32_e32 v248, 7, v217
	v_and_b32_e32 v249, 0x60, v187
	v_lshl_or_b32 v249, s19, 8, v249
	v_lshl_add_u32 v249, v248, 2, v249
	v_mul_lo_u32 v246, s86, v246
	v_add_u32_e32 v246, v246, v249
	v_lshlrev_b32_e32 v175, 2, v246
	v_add_u32_e32 v210, 0x10000, v175
	v_lshrrev_b32_e32 v249, 4, v217
	v_lshlrev_b32_e32 v249, 1, v249
	v_xor_b32_e32 v249, v249, v248
	v_lshlrev_b32_e32 v249, 4, v249
	v_lshl_add_u32 v249, v248, 7, v249
	v_and_b32_e32 v250, 8, v217
	v_lshl_add_u32 v249, v250, 10, v249
	v_add_u32_e32 v211, s31, v249
	global_load_dwordx4 v[136:139], v174, s[52:53]
	global_load_dwordx4 v[140:143], v174, s[52:53] offset:256
	v_add_u32_e32 v174, 0x10000, v174
	global_load_dwordx4 v[158:161], v174, s[52:53]
	global_load_dwordx4 v[162:165], v174, s[52:53] offset:256
	v_add_u32_e32 v174, 0x10000, v174
	global_load_dwordx4 v[166:169], v174, s[52:53]
	global_load_dwordx4 v[170:173], v174, s[52:53] offset:256
	v_add_u32_e32 v174, 0x10000, v174
	global_load_dwordx4 v[190:193], v174, s[52:53]
	global_load_dwordx4 v[194:197], v174, s[52:53] offset:256
	v_add_u32_e32 v174, 0x50000, v174
	global_load_dwordx4 v[198:201], v174, s[52:53]
	global_load_dwordx4 v[202:205], v174, s[52:53] offset:256
	v_add_u32_e32 v174, 0x10000, v174
	global_load_dwordx4 v[206:209], v174, s[52:53]
	global_load_dwordx4 v[224:227], v174, s[52:53] offset:256
	v_add_u32_e32 v174, 0x10000, v174
	global_load_dwordx4 v[228:231], v174, s[52:53]
	global_load_dwordx4 v[232:235], v174, s[52:53] offset:256
	v_add_u32_e32 v174, 0x10000, v174
	global_load_dwordx4 v[236:239], v174, s[52:53]
	global_load_dwordx4 v[240:243], v174, s[52:53] offset:256
	v_xor_b32_e32 v250, v248, v247
	v_lshlrev_b32_e32 v250, 4, v250
	v_lshl_add_u32 v250, v247, 7, v250
	v_add_u32_e32 v174, s31, v250
	s_waitcnt vmcnt(15)
	v_lshlrev_b32_e32 v244, 16, v136
	v_and_b32_e32 v245, 0xffff0000, v136
	v_lshlrev_b32_e32 v246, 16, v137
	v_and_b32_e32 v247, 0xffff0000, v137
	v_lshlrev_b32_e32 v248, 16, v138
	v_and_b32_e32 v249, 0xffff0000, v138
	v_lshlrev_b32_e32 v250, 16, v139
	v_and_b32_e32 v251, 0xffff0000, v139
	v_pk_fma_f32 v[132:133], s[76:77], v[132:133], v[244:245]
	v_pk_fma_f32 v[134:135], s[84:85], v[134:135], v[246:247]
	v_pk_fma_f32 v[128:129], s[76:77], v[128:129], v[248:249]
	v_pk_fma_f32 v[130:131], s[84:85], v[130:131], v[250:251]
	v_xor_b32_e32 v244, 16, v211
	ds_write_b128 v211, v[132:135] offset:49152
	ds_write_b128 v244, v[128:131] offset:49152
	s_waitcnt lgkmcnt(0)
	ds_read_b128 v[132:135], v174 offset:49152
	ds_read_b128 v[128:131], v174 offset:57344
	s_waitcnt lgkmcnt(0)
	global_store_dwordx4 v175, v[132:135], s[54:55] nt
	global_store_dwordx4 v210, v[128:131], s[54:55] nt
	s_waitcnt vmcnt(16)
	v_lshlrev_b32_e32 v244, 16, v140
	v_and_b32_e32 v245, 0xffff0000, v140
	v_lshlrev_b32_e32 v246, 16, v141
	v_and_b32_e32 v247, 0xffff0000, v141
	v_lshlrev_b32_e32 v248, 16, v142
	v_and_b32_e32 v249, 0xffff0000, v142
	v_lshlrev_b32_e32 v250, 16, v143
	v_and_b32_e32 v251, 0xffff0000, v143
	v_pk_fma_f32 v[124:125], s[76:77], v[124:125], v[244:245]
	v_pk_fma_f32 v[126:127], s[84:85], v[126:127], v[246:247]
	v_pk_fma_f32 v[120:121], s[76:77], v[120:121], v[248:249]
	v_pk_fma_f32 v[122:123], s[84:85], v[122:123], v[250:251]
	v_xor_b32_e32 v244, 16, v211
	ds_write_b128 v211, v[124:127] offset:49152
	ds_write_b128 v244, v[120:123] offset:49152
	s_waitcnt lgkmcnt(0)
	ds_read_b128 v[124:127], v174 offset:49152
	ds_read_b128 v[120:123], v174 offset:57344
	s_waitcnt lgkmcnt(0)
	global_store_dwordx4 v175, v[124:127], s[54:55] offset:512 nt
	global_store_dwordx4 v210, v[120:123], s[54:55] offset:512 nt
	v_add_u32_e32 v175, 0x20000, v175
	v_add_u32_e32 v210, 0x20000, v210
	s_waitcnt vmcnt(17)
	v_lshlrev_b32_e32 v244, 16, v158
	v_and_b32_e32 v245, 0xffff0000, v158
	v_lshlrev_b32_e32 v246, 16, v159
	v_and_b32_e32 v247, 0xffff0000, v159
	v_lshlrev_b32_e32 v248, 16, v160
	v_and_b32_e32 v249, 0xffff0000, v160
	v_lshlrev_b32_e32 v250, 16, v161
	v_and_b32_e32 v251, 0xffff0000, v161
	v_pk_fma_f32 v[116:117], s[76:77], v[116:117], v[244:245]
	v_pk_fma_f32 v[118:119], s[84:85], v[118:119], v[246:247]
	v_pk_fma_f32 v[106:107], s[76:77], v[106:107], v[248:249]
	v_pk_fma_f32 v[108:109], s[84:85], v[108:109], v[250:251]
	v_xor_b32_e32 v244, 16, v211
	ds_write_b128 v211, v[116:119] offset:49152
	ds_write_b128 v244, v[106:109] offset:49152
	s_waitcnt lgkmcnt(0)
	ds_read_b128 v[116:119], v174 offset:49152
	ds_read_b128 v[106:109], v174 offset:57344
	s_waitcnt lgkmcnt(0)
	global_store_dwordx4 v175, v[116:119], s[54:55] nt
	global_store_dwordx4 v210, v[106:109], s[54:55] nt
	s_waitcnt vmcnt(18)
	v_lshlrev_b32_e32 v244, 16, v162
	v_and_b32_e32 v245, 0xffff0000, v162
	v_lshlrev_b32_e32 v246, 16, v163
	v_and_b32_e32 v247, 0xffff0000, v163
	v_lshlrev_b32_e32 v248, 16, v164
	v_and_b32_e32 v249, 0xffff0000, v164
	v_lshlrev_b32_e32 v250, 16, v165
	v_and_b32_e32 v251, 0xffff0000, v165
	v_pk_fma_f32 v[102:103], s[76:77], v[102:103], v[244:245]
	v_pk_fma_f32 v[104:105], s[84:85], v[104:105], v[246:247]
	v_pk_fma_f32 v[98:99], s[76:77], v[98:99], v[248:249]
	v_pk_fma_f32 v[100:101], s[84:85], v[100:101], v[250:251]
	v_xor_b32_e32 v244, 16, v211
	ds_write_b128 v211, v[102:105] offset:49152
	ds_write_b128 v244, v[98:101] offset:49152
	s_waitcnt lgkmcnt(0)
	ds_read_b128 v[102:105], v174 offset:49152
	ds_read_b128 v[98:101], v174 offset:57344
	s_waitcnt lgkmcnt(0)
;     __device__ __forceinline__ void operator()(const f32x4 (&acc)[2][2][4][2], const Unit& u, int wr, int wc, int fr, int fq) const {
;     ...
;                         if (base_bf) { const u32x4 t = *(const u32x4*)(base_bf + off + bj * HALF);
;                             b0 = (f32x4){__uint_as_float(t.x << 16), __uint_as_float(t.x & 0xffff0000u), __uint_as_float(t.y << 16), __uint_as_float(t.y & 0xffff0000u)};
;                             b1 = (f32x4){__uint_as_float(t.z << 16), __uint_as_float(t.z & 0xffff0000u), __uint_as_float(t.w << 16), __uint_as_float(t.w & 0xffff0000u)}; }
;                         else { b0 = *(const f32x4*)(base + off + bj * HALF); b1 = *(const f32x4*)(base + off + bj * HALF + 4); }
;                         const f32x4 o0 = b0 + acc[ai][bj][m][0] * alpha, o1 = b1 + acc[ai][bj][m][1] * alpha;
;                         if (out) { *(f32x4*)(out + off + bj * HALF) = o0; *(f32x4*)(out + off + bj * HALF + 4) = o1; }
	global_store_dwordx4 v175, v[102:105], s[54:55] offset:512 nt
	global_store_dwordx4 v210, v[98:101], s[54:55] offset:512 nt
	v_add_u32_e32 v175, 0x20000, v175
	v_add_u32_e32 v210, 0x20000, v210
	s_waitcnt vmcnt(19)
	v_lshlrev_b32_e32 v244, 16, v166
	v_and_b32_e32 v245, 0xffff0000, v166
	v_lshlrev_b32_e32 v246, 16, v167
	v_and_b32_e32 v247, 0xffff0000, v167
	v_lshlrev_b32_e32 v248, 16, v168
	v_and_b32_e32 v249, 0xffff0000, v168
	v_lshlrev_b32_e32 v250, 16, v169
	v_and_b32_e32 v251, 0xffff0000, v169
	v_pk_fma_f32 v[94:95], s[76:77], v[94:95], v[244:245]
	v_pk_fma_f32 v[96:97], s[84:85], v[96:97], v[246:247]
	v_pk_fma_f32 v[90:91], s[76:77], v[90:91], v[248:249]
	v_pk_fma_f32 v[92:93], s[84:85], v[92:93], v[250:251]
	v_xor_b32_e32 v244, 16, v211
	ds_write_b128 v211, v[94:97] offset:49152
	ds_write_b128 v244, v[90:93] offset:49152
	s_waitcnt lgkmcnt(0)
	ds_read_b128 v[94:97], v174 offset:49152
	ds_read_b128 v[90:93], v174 offset:57344
	s_waitcnt lgkmcnt(0)
	global_store_dwordx4 v175, v[94:97], s[54:55] nt
	global_store_dwordx4 v210, v[90:93], s[54:55] nt
	s_waitcnt vmcnt(20)
	v_lshlrev_b32_e32 v244, 16, v170
	v_and_b32_e32 v245, 0xffff0000, v170
	v_lshlrev_b32_e32 v246, 16, v171
	v_and_b32_e32 v247, 0xffff0000, v171
	v_lshlrev_b32_e32 v248, 16, v172
	v_and_b32_e32 v249, 0xffff0000, v172
	v_lshlrev_b32_e32 v250, 16, v173
	v_and_b32_e32 v251, 0xffff0000, v173
	v_pk_fma_f32 v[86:87], s[76:77], v[86:87], v[244:245]
	v_pk_fma_f32 v[88:89], s[84:85], v[88:89], v[246:247]
	v_pk_fma_f32 v[82:83], s[76:77], v[82:83], v[248:249]
	v_pk_fma_f32 v[84:85], s[84:85], v[84:85], v[250:251]
	v_xor_b32_e32 v244, 16, v211
	ds_write_b128 v211, v[86:89] offset:49152
	ds_write_b128 v244, v[82:85] offset:49152
	s_waitcnt lgkmcnt(0)
	ds_read_b128 v[86:89], v174 offset:49152
	ds_read_b128 v[82:85], v174 offset:57344
	s_waitcnt lgkmcnt(0)
	global_store_dwordx4 v175, v[86:89], s[54:55] offset:512 nt
	global_store_dwordx4 v210, v[82:85], s[54:55] offset:512 nt
	v_add_u32_e32 v175, 0x20000, v175
	v_add_u32_e32 v210, 0x20000, v210
	s_waitcnt vmcnt(21)
	v_lshlrev_b32_e32 v244, 16, v190
	v_and_b32_e32 v245, 0xffff0000, v190
	v_lshlrev_b32_e32 v246, 16, v191
	v_and_b32_e32 v247, 0xffff0000, v191
	v_lshlrev_b32_e32 v248, 16, v192
	v_and_b32_e32 v249, 0xffff0000, v192
	v_lshlrev_b32_e32 v250, 16, v193
	v_and_b32_e32 v251, 0xffff0000, v193
	v_pk_fma_f32 v[78:79], s[76:77], v[78:79], v[244:245]
	v_pk_fma_f32 v[80:81], s[84:85], v[80:81], v[246:247]
	v_pk_fma_f32 v[74:75], s[76:77], v[74:75], v[248:249]
	v_pk_fma_f32 v[76:77], s[84:85], v[76:77], v[250:251]
	v_xor_b32_e32 v244, 16, v211
	ds_write_b128 v211, v[78:81] offset:49152
	ds_write_b128 v244, v[74:77] offset:49152
	s_waitcnt lgkmcnt(0)
	ds_read_b128 v[78:81], v174 offset:49152
	ds_read_b128 v[74:77], v174 offset:57344
	s_waitcnt lgkmcnt(0)
	global_store_dwordx4 v175, v[78:81], s[54:55] nt
	global_store_dwordx4 v210, v[74:77], s[54:55] nt
	s_waitcnt vmcnt(22)
	v_lshlrev_b32_e32 v244, 16, v194
	v_and_b32_e32 v245, 0xffff0000, v194
	v_lshlrev_b32_e32 v246, 16, v195
	v_and_b32_e32 v247, 0xffff0000, v195
	v_lshlrev_b32_e32 v248, 16, v196
	v_and_b32_e32 v249, 0xffff0000, v196
	v_lshlrev_b32_e32 v250, 16, v197
	v_and_b32_e32 v251, 0xffff0000, v197
	v_pk_fma_f32 v[70:71], s[76:77], v[70:71], v[244:245]
	v_pk_fma_f32 v[72:73], s[84:85], v[72:73], v[246:247]
	v_pk_fma_f32 v[66:67], s[76:77], v[66:67], v[248:249]
	v_pk_fma_f32 v[68:69], s[84:85], v[68:69], v[250:251]
	v_xor_b32_e32 v244, 16, v211
	ds_write_b128 v211, v[70:73] offset:49152
	ds_write_b128 v244, v[66:69] offset:49152
	s_waitcnt lgkmcnt(0)
	ds_read_b128 v[70:73], v174 offset:49152
	ds_read_b128 v[66:69], v174 offset:57344
	s_waitcnt lgkmcnt(0)
	global_store_dwordx4 v175, v[70:73], s[54:55] offset:512 nt
	global_store_dwordx4 v210, v[66:69], s[54:55] offset:512 nt
	v_add_u32_e32 v175, 0xa0000, v175
	v_add_u32_e32 v210, 0xa0000, v210
	s_waitcnt vmcnt(23)
	v_lshlrev_b32_e32 v244, 16, v198
	v_and_b32_e32 v245, 0xffff0000, v198
	v_lshlrev_b32_e32 v246, 16, v199
	v_and_b32_e32 v247, 0xffff0000, v199
	v_lshlrev_b32_e32 v248, 16, v200
	v_and_b32_e32 v249, 0xffff0000, v200
	v_lshlrev_b32_e32 v250, 16, v201
	v_and_b32_e32 v251, 0xffff0000, v201
	v_pk_fma_f32 v[62:63], s[76:77], v[62:63], v[244:245]
	v_pk_fma_f32 v[64:65], s[84:85], v[64:65], v[246:247]
	v_pk_fma_f32 v[58:59], s[76:77], v[58:59], v[248:249]
	v_pk_fma_f32 v[60:61], s[84:85], v[60:61], v[250:251]
	v_xor_b32_e32 v244, 16, v211
	ds_write_b128 v211, v[62:65] offset:49152
	ds_write_b128 v244, v[58:61] offset:49152
	s_waitcnt lgkmcnt(0)
	ds_read_b128 v[62:65], v174 offset:49152
	ds_read_b128 v[58:61], v174 offset:57344
	s_waitcnt lgkmcnt(0)
	global_store_dwordx4 v175, v[62:65], s[54:55] nt
	global_store_dwordx4 v210, v[58:61], s[54:55] nt
	s_waitcnt vmcnt(24)
	v_lshlrev_b32_e32 v244, 16, v202
	v_and_b32_e32 v245, 0xffff0000, v202
	v_lshlrev_b32_e32 v246, 16, v203
	v_and_b32_e32 v247, 0xffff0000, v203
	v_lshlrev_b32_e32 v248, 16, v204
	v_and_b32_e32 v249, 0xffff0000, v204
	v_lshlrev_b32_e32 v250, 16, v205
	v_and_b32_e32 v251, 0xffff0000, v205
	v_pk_fma_f32 v[54:55], s[76:77], v[54:55], v[244:245]
	v_pk_fma_f32 v[56:57], s[84:85], v[56:57], v[246:247]
	v_pk_fma_f32 v[50:51], s[76:77], v[50:51], v[248:249]
	v_pk_fma_f32 v[52:53], s[84:85], v[52:53], v[250:251]
	v_xor_b32_e32 v244, 16, v211
	ds_write_b128 v211, v[54:57] offset:49152
	ds_write_b128 v244, v[50:53] offset:49152
	s_waitcnt lgkmcnt(0)
	ds_read_b128 v[54:57], v174 offset:49152
	ds_read_b128 v[50:53], v174 offset:57344
	s_waitcnt lgkmcnt(0)
;     __device__ __forceinline__ void operator()(const f32x4 (&acc)[2][2][4][2], const Unit& u, int wr, int wc, int fr, int fq) const {
;     ...
;                         if (base_bf) { const u32x4 t = *(const u32x4*)(base_bf + off + bj * HALF);
;                             b0 = (f32x4){__uint_as_float(t.x << 16), __uint_as_float(t.x & 0xffff0000u), __uint_as_float(t.y << 16), __uint_as_float(t.y & 0xffff0000u)};
;                             b1 = (f32x4){__uint_as_float(t.z << 16), __uint_as_float(t.z & 0xffff0000u), __uint_as_float(t.w << 16), __uint_as_float(t.w & 0xffff0000u)}; }
;                         else { b0 = *(const f32x4*)(base + off + bj * HALF); b1 = *(const f32x4*)(base + off + bj * HALF + 4); }
;                         const f32x4 o0 = b0 + acc[ai][bj][m][0] * alpha, o1 = b1 + acc[ai][bj][m][1] * alpha;
;                         if (out) { *(f32x4*)(out + off + bj * HALF) = o0; *(f32x4*)(out + off + bj * HALF + 4) = o1; }
	global_store_dwordx4 v175, v[54:57], s[54:55] offset:512 nt
	global_store_dwordx4 v210, v[50:53], s[54:55] offset:512 nt
	v_add_u32_e32 v175, 0x20000, v175
	v_add_u32_e32 v210, 0x20000, v210
	s_waitcnt vmcnt(25)
	v_lshlrev_b32_e32 v244, 16, v206
	v_and_b32_e32 v245, 0xffff0000, v206
	v_lshlrev_b32_e32 v246, 16, v207
	v_and_b32_e32 v247, 0xffff0000, v207
	v_lshlrev_b32_e32 v248, 16, v208
	v_and_b32_e32 v249, 0xffff0000, v208
	v_lshlrev_b32_e32 v250, 16, v209
	v_and_b32_e32 v251, 0xffff0000, v209
	v_pk_fma_f32 v[46:47], s[76:77], v[46:47], v[244:245]
	v_pk_fma_f32 v[48:49], s[84:85], v[48:49], v[246:247]
	v_pk_fma_f32 v[42:43], s[76:77], v[42:43], v[248:249]
	v_pk_fma_f32 v[44:45], s[84:85], v[44:45], v[250:251]
	v_xor_b32_e32 v244, 16, v211
	ds_write_b128 v211, v[46:49] offset:49152
	ds_write_b128 v244, v[42:45] offset:49152
	s_waitcnt lgkmcnt(0)
	ds_read_b128 v[46:49], v174 offset:49152
	ds_read_b128 v[42:45], v174 offset:57344
	s_waitcnt lgkmcnt(0)
	global_store_dwordx4 v175, v[46:49], s[54:55] nt
	global_store_dwordx4 v210, v[42:45], s[54:55] nt
	s_waitcnt vmcnt(26)
	v_lshlrev_b32_e32 v244, 16, v224
	v_and_b32_e32 v245, 0xffff0000, v224
	v_lshlrev_b32_e32 v246, 16, v225
	v_and_b32_e32 v247, 0xffff0000, v225
	v_lshlrev_b32_e32 v248, 16, v226
	v_and_b32_e32 v249, 0xffff0000, v226
	v_lshlrev_b32_e32 v250, 16, v227
	v_and_b32_e32 v251, 0xffff0000, v227
	v_pk_fma_f32 v[38:39], s[76:77], v[38:39], v[244:245]
	v_pk_fma_f32 v[40:41], s[84:85], v[40:41], v[246:247]
	v_pk_fma_f32 v[34:35], s[76:77], v[34:35], v[248:249]
	v_pk_fma_f32 v[36:37], s[84:85], v[36:37], v[250:251]
	v_xor_b32_e32 v244, 16, v211
	ds_write_b128 v211, v[38:41] offset:49152
	ds_write_b128 v244, v[34:37] offset:49152
	s_waitcnt lgkmcnt(0)
	ds_read_b128 v[38:41], v174 offset:49152
	ds_read_b128 v[34:37], v174 offset:57344
	s_waitcnt lgkmcnt(0)
	global_store_dwordx4 v175, v[38:41], s[54:55] offset:512 nt
	global_store_dwordx4 v210, v[34:37], s[54:55] offset:512 nt
	v_add_u32_e32 v175, 0x20000, v175
	v_add_u32_e32 v210, 0x20000, v210
	s_waitcnt vmcnt(27)
	v_lshlrev_b32_e32 v244, 16, v228
	v_and_b32_e32 v245, 0xffff0000, v228
	v_lshlrev_b32_e32 v246, 16, v229
	v_and_b32_e32 v247, 0xffff0000, v229
	v_lshlrev_b32_e32 v248, 16, v230
	v_and_b32_e32 v249, 0xffff0000, v230
	v_lshlrev_b32_e32 v250, 16, v231
	v_and_b32_e32 v251, 0xffff0000, v231
	v_pk_fma_f32 v[30:31], s[76:77], v[30:31], v[244:245]
	v_pk_fma_f32 v[32:33], s[84:85], v[32:33], v[246:247]
	v_pk_fma_f32 v[26:27], s[76:77], v[26:27], v[248:249]
	v_pk_fma_f32 v[28:29], s[84:85], v[28:29], v[250:251]
	v_xor_b32_e32 v244, 16, v211
	ds_write_b128 v211, v[30:33] offset:49152
	ds_write_b128 v244, v[26:29] offset:49152
	s_waitcnt lgkmcnt(0)
	ds_read_b128 v[30:33], v174 offset:49152
	ds_read_b128 v[26:29], v174 offset:57344
	s_waitcnt lgkmcnt(0)
	global_store_dwordx4 v175, v[30:33], s[54:55] nt
	global_store_dwordx4 v210, v[26:29], s[54:55] nt
	s_waitcnt vmcnt(28)
	v_lshlrev_b32_e32 v244, 16, v232
	v_and_b32_e32 v245, 0xffff0000, v232
	v_lshlrev_b32_e32 v246, 16, v233
	v_and_b32_e32 v247, 0xffff0000, v233
	v_lshlrev_b32_e32 v248, 16, v234
	v_and_b32_e32 v249, 0xffff0000, v234
	v_lshlrev_b32_e32 v250, 16, v235
	v_and_b32_e32 v251, 0xffff0000, v235
	v_pk_fma_f32 v[22:23], s[76:77], v[22:23], v[244:245]
	v_pk_fma_f32 v[24:25], s[84:85], v[24:25], v[246:247]
	v_pk_fma_f32 v[18:19], s[76:77], v[18:19], v[248:249]
	v_pk_fma_f32 v[20:21], s[84:85], v[20:21], v[250:251]
	v_xor_b32_e32 v244, 16, v211
	ds_write_b128 v211, v[22:25] offset:49152
	ds_write_b128 v244, v[18:21] offset:49152
	s_waitcnt lgkmcnt(0)
	ds_read_b128 v[22:25], v174 offset:49152
	ds_read_b128 v[18:21], v174 offset:57344
	s_waitcnt lgkmcnt(0)
	global_store_dwordx4 v175, v[22:25], s[54:55] offset:512 nt
	global_store_dwordx4 v210, v[18:21], s[54:55] offset:512 nt
	v_add_u32_e32 v175, 0x20000, v175
	v_add_u32_e32 v210, 0x20000, v210
	s_waitcnt vmcnt(29)
	v_lshlrev_b32_e32 v244, 16, v236
	v_and_b32_e32 v245, 0xffff0000, v236
	v_lshlrev_b32_e32 v246, 16, v237
	v_and_b32_e32 v247, 0xffff0000, v237
	v_lshlrev_b32_e32 v248, 16, v238
	v_and_b32_e32 v249, 0xffff0000, v238
	v_lshlrev_b32_e32 v250, 16, v239
	v_and_b32_e32 v251, 0xffff0000, v239
	v_pk_fma_f32 v[14:15], s[76:77], v[14:15], v[244:245]
	v_pk_fma_f32 v[16:17], s[84:85], v[16:17], v[246:247]
	v_pk_fma_f32 v[10:11], s[76:77], v[10:11], v[248:249]
	v_pk_fma_f32 v[12:13], s[84:85], v[12:13], v[250:251]
	v_xor_b32_e32 v244, 16, v211
	ds_write_b128 v211, v[14:17] offset:49152
	ds_write_b128 v244, v[10:13] offset:49152
	s_waitcnt lgkmcnt(0)
	ds_read_b128 v[14:17], v174 offset:49152
	ds_read_b128 v[10:13], v174 offset:57344
	s_waitcnt lgkmcnt(0)
	global_store_dwordx4 v175, v[14:17], s[54:55] nt
	global_store_dwordx4 v210, v[10:13], s[54:55] nt
	s_waitcnt vmcnt(30)
	v_lshlrev_b32_e32 v244, 16, v240
	v_and_b32_e32 v245, 0xffff0000, v240
	v_lshlrev_b32_e32 v246, 16, v241
	v_and_b32_e32 v247, 0xffff0000, v241
	v_lshlrev_b32_e32 v248, 16, v242
	v_and_b32_e32 v249, 0xffff0000, v242
	v_lshlrev_b32_e32 v250, 16, v243
	v_and_b32_e32 v251, 0xffff0000, v243
	v_pk_fma_f32 v[6:7], s[76:77], v[6:7], v[244:245]
	v_pk_fma_f32 v[8:9], s[84:85], v[8:9], v[246:247]
	v_pk_fma_f32 v[2:3], s[76:77], v[2:3], v[248:249]
	v_pk_fma_f32 v[4:5], s[84:85], v[4:5], v[250:251]
	v_xor_b32_e32 v244, 16, v211
	ds_write_b128 v211, v[6:9] offset:49152
	ds_write_b128 v244, v[2:5] offset:49152
	s_waitcnt lgkmcnt(0)
	ds_read_b128 v[6:9], v174 offset:49152
	ds_read_b128 v[2:5], v174 offset:57344
	s_waitcnt lgkmcnt(0)
	global_store_dwordx4 v175, v[6:9], s[54:55] offset:512 nt
	global_store_dwordx4 v210, v[2:5], s[54:55] offset:512 nt
